# attention: T5 bias LDS reads batched (preload after barrier) + v_cndmask instead of 34 guarded serialized reads
# speedup vs baseline: 1.0603x; 1.0032x over previous
; __device__ __forceinline__ void attn_item(const Ctx& C, int it, int itn, u32x4 (&kv)[4], u32x4 (&vv)[4], u32x4 (&qv)[2]) {
;     ...
;     const int fr = lane & 15, quad = lane >> 4;
;     bf16x8 qf[2];
;     qf[0] = *(const bf16x8*)(Qs + (16 * w + fr) * 72 + 8 * quad); qf[1] = *(const bf16x8*)(Qs + (16 * w + fr) * 72 + 32 + 8 * quad);
;     f32x4 sc[9];
; #pragma unroll
;     for (int kt = 0; kt < 9; ++kt) { const bf16_t* kr = Ks + (16 * (w + kt) + fr) * 72 + 8 * quad;
;         const bf16x8 k0 = *(const bf16x8*)kr, k1 = *(const bf16x8*)(kr + 32);
;         f32x4 z4 = {0.f, 0.f, 0.f, 0.f};
;         z4 = __builtin_amdgcn_mfma_f32_16x16x32_bf16(k0, qf[0], z4, 0, 0, 0);
;         sc[kt] = __builtin_amdgcn_mfma_f32_16x16x32_bf16(k1, qf[1], z4, 0, 0, 0); }
;     const int a = 16 * w + fr;
;     float mx = -1e30f;
; #pragma unroll
;     for (int kt = 0; kt < 9; ++kt)
; #pragma unroll
;         for (int rg = 0; rg < 4; ++rg) { const int cidx = 16 * (w + kt) + 4 * quad + rg, rel = cidx - 64 - a, ik = 128 * jb - 64 + cidx;
;             const bool valid = (rel >= -64) && (rel <= 64) && (ik >= 0) && (ik < n);
;             const int bi = rel < -64 ? 0 : (rel > 64 ? 128 : rel + 64);
;             const float s = valid ? sc[kt][rg] * 0.125f + bt[bi] : -1e30f;
;             sc[kt][rg] = s; mx = fmaxf(mx, s); }
.LBB0_359:
	s_waitcnt lgkmcnt(0)
	s_barrier
	v_mov_b32_e32 v178, 0xf149f2ca
	ds_read_b32 v179, v98
	ds_read_b32 v180, v100
	ds_read_b32 v181, v102
	ds_read_b32 v188, v104
	ds_read_b32 v189, v106
	ds_read_b32 v190, v108
	ds_read_b32 v191, v110
	ds_read_b32 v212, v112
	ds_read_b32 v213, v114
	ds_read_b32 v214, v116
	ds_read_b32 v215, v118
	ds_read_b32 v223, v120
	ds_read_b32 v228, v122
	ds_read_b32 v229, v124
	ds_read_b32 v230, v126
	ds_read_b32 v231, v128
	ds_read_b32 v232, v130
	ds_read_b32 v233, v132
	ds_read_b32 v234, v134
	ds_read_b32 v235, v136
	ds_read_b32 v236, v138
	ds_read_b32 v237, v140
	ds_read_b32 v238, v142
	ds_read_b32 v240, v144
	ds_read_b32 v241, v146
	ds_read_b32 v242, v148
	ds_read_b32 v243, v150
	ds_read_b32 v244, v152
	ds_read_b32 v245, v154
	ds_read_b32 v246, v156
	ds_read_b32 v247, v158
	ds_read_b32 v248, v160
	ds_read_b32 v249, v162
	ds_read_b32 v250, v164
	ds_read_b128 v[40:43], v85 offset:36864
	ds_read_b128 v[194:197], v85 offset:36928
	ds_read_b128 v[44:47], v87
	ds_read_b128 v[48:51], v87 offset:64
	s_waitcnt lgkmcnt(1)
	v_mfma_f32_16x16x32_bf16 v[44:47], v[44:47], v[40:43], 0
	s_lshr_b32 s0, 32, s52
	s_and_b32 s47, s36, 31
	s_add_i32 s0, s0, -1
	s_waitcnt lgkmcnt(0)
	v_mfma_f32_16x16x32_bf16 v[74:77], v[48:51], v[194:197], v[44:47]
	s_nop 2
	ds_read_b128 v[44:47], v173
	ds_read_b128 v[48:51], v173 offset:64
	s_and_b32 s0, s0, s47
	s_lshl_b32 s46, s0, 7
	s_waitcnt lgkmcnt(1)
	v_mfma_f32_16x16x32_bf16 v[44:47], v[44:47], v[40:43], 0
	s_sub_i32 s48, s46, 64
	v_add_u32_e32 v64, s48, v89
	v_readlane_b32 s0, v255, 7
	s_waitcnt lgkmcnt(0)
	v_mfma_f32_16x16x32_bf16 v[70:73], v[48:51], v[194:197], v[44:47]
	s_nop 2
	ds_read_b128 v[44:47], v174
	ds_read_b128 v[48:51], v174 offset:64
	s_lshr_b32 s53, 0x1000, s52
	v_cmp_lt_i32_e32 vcc, -1, v64
	s_waitcnt lgkmcnt(1)
	v_mfma_f32_16x16x32_bf16 v[44:47], v[44:47], v[40:43], 0
	v_readlane_b32 s1, v255, 8
	s_and_b64 s[0:1], s[0:1], vcc
	v_cmp_gt_i32_e32 vcc, s53, v64
	s_waitcnt lgkmcnt(0)
	v_mfma_f32_16x16x32_bf16 v[66:69], v[48:51], v[194:197], v[44:47]
	s_nop 2
	ds_read_b128 v[44:47], v175
	ds_read_b128 v[48:51], v175 offset:64
	s_and_b64 s[68:69], s[0:1], vcc
	s_waitcnt lgkmcnt(1)
	v_mfma_f32_16x16x32_bf16 v[44:47], v[44:47], v[40:43], 0
	s_waitcnt lgkmcnt(0)
	v_mfma_f32_16x16x32_bf16 v[60:63], v[48:51], v[194:197], v[44:47]
	s_nop 5
	ds_read_b128 v[44:47], v176
	ds_read_b128 v[48:51], v176 offset:64
	s_waitcnt lgkmcnt(1)
	v_mfma_f32_16x16x32_bf16 v[44:47], v[44:47], v[40:43], 0
	s_waitcnt lgkmcnt(0)
	v_mfma_f32_16x16x32_bf16 v[56:59], v[48:51], v[194:197], v[44:47]
	s_nop 5
	ds_read_b128 v[44:47], v177
	ds_read_b128 v[48:51], v177 offset:64
	s_waitcnt lgkmcnt(1)
	v_mfma_f32_16x16x32_bf16 v[44:47], v[44:47], v[40:43], 0
	s_waitcnt lgkmcnt(0)
	v_mfma_f32_16x16x32_bf16 v[52:55], v[48:51], v[194:197], v[44:47]
	s_nop 5
	ds_read_b128 v[44:47], v183
	ds_read_b128 v[48:51], v183 offset:64
	s_waitcnt lgkmcnt(1)
	v_mfma_f32_16x16x32_bf16 v[44:47], v[44:47], v[40:43], 0
	s_waitcnt lgkmcnt(0)
	v_mfma_f32_16x16x32_bf16 v[48:51], v[48:51], v[194:197], v[44:47]
	s_nop 5
	ds_read_b128 v[44:47], v192
	ds_read_b128 v[198:201], v192 offset:64
	s_waitcnt lgkmcnt(1)
	v_mfma_f32_16x16x32_bf16 v[44:47], v[44:47], v[40:43], 0
	s_waitcnt lgkmcnt(0)
	v_mfma_f32_16x16x32_bf16 v[44:47], v[198:201], v[194:197], v[44:47]
	ds_read_b128 v[198:201], v193
	ds_read_b128 v[202:205], v193 offset:64
	s_waitcnt lgkmcnt(1)
	v_mfma_f32_16x16x32_bf16 v[40:43], v[198:201], v[40:43], 0
	s_waitcnt lgkmcnt(0)
	v_mfma_f32_16x16x32_bf16 v[40:43], v[202:205], v[194:197], v[40:43]
	v_fmac_f32_e32 v179, 0x3e000000, v74
	v_cndmask_b32_e64 v195, v178, v179, s[68:69]
	v_add_u32_e32 v64, s48, v99
	v_readlane_b32 s0, v255, 9
	v_cmp_lt_i32_e32 vcc, -1, v64
	v_readlane_b32 s1, v255, 10
	s_and_b64 s[0:1], s[0:1], vcc
	v_cmp_gt_i32_e32 vcc, s53, v64
	s_and_b64 s[68:69], s[0:1], vcc
	v_fmac_f32_e32 v180, 0x3e000000, v75
	v_cndmask_b32_e64 v91, v178, v180, s[68:69]
	v_add_u32_e32 v64, s48, v101
	v_readlane_b32 s0, v255, 11
	v_cmp_lt_i32_e32 vcc, -1, v64
	v_readlane_b32 s1, v255, 12
	s_and_b64 s[0:1], s[0:1], vcc
	v_cmp_gt_i32_e32 vcc, s53, v64
	s_and_b64 s[68:69], s[0:1], vcc
	v_fmac_f32_e32 v181, 0x3e000000, v76
	v_cndmask_b32_e64 v194, v178, v181, s[68:69]
	v_add_u32_e32 v64, s48, v103
	v_readlane_b32 s0, v255, 13
	v_cmp_lt_i32_e32 vcc, -1, v64
	v_readlane_b32 s1, v255, 14
	s_and_b64 s[0:1], s[0:1], vcc
	v_cmp_gt_i32_e32 vcc, s53, v64
	s_and_b64 s[68:69], s[0:1], vcc
	v_fmac_f32_e32 v188, 0x3e000000, v77
	v_cndmask_b32_e64 v79, v178, v188, s[68:69]
	v_add_u32_e32 v64, s48, v105
	v_readlane_b32 s0, v255, 15
	v_cmp_lt_i32_e32 vcc, -1, v64
	v_readlane_b32 s1, v255, 16
	s_and_b64 s[0:1], s[0:1], vcc
	v_cmp_gt_i32_e32 vcc, s53, v64
	s_and_b64 s[68:69], s[0:1], vcc
	v_fmac_f32_e32 v189, 0x3e000000, v70
	v_cndmask_b32_e64 v74, v178, v189, s[68:69]
	v_add_u32_e32 v70, s48, v107
	v_readlane_b32 s0, v255, 17
	v_cmp_lt_i32_e32 vcc, -1, v70
	v_readlane_b32 s1, v255, 18
	s_and_b64 s[0:1], s[0:1], vcc
	v_cmp_gt_i32_e32 vcc, s53, v70
	s_and_b64 s[68:69], s[0:1], vcc
	v_fmac_f32_e32 v190, 0x3e000000, v71
	v_cndmask_b32_e64 v64, v178, v190, s[68:69]
	v_add_u32_e32 v70, s48, v109
	v_readlane_b32 s0, v255, 19
	v_cmp_lt_i32_e32 vcc, -1, v70
	v_readlane_b32 s1, v255, 20
	s_and_b64 s[0:1], s[0:1], vcc
	v_cmp_gt_i32_e32 vcc, s53, v70
	s_and_b64 s[68:69], s[0:1], vcc
	v_fmac_f32_e32 v191, 0x3e000000, v72
	v_cndmask_b32_e64 v75, v178, v191, s[68:69]
	v_add_u32_e32 v71, s48, v111
	v_readlane_b32 s0, v255, 21
	v_cmp_lt_i32_e32 vcc, -1, v71
	v_readlane_b32 s1, v255, 22
	s_and_b64 s[0:1], s[0:1], vcc
	v_cmp_gt_i32_e32 vcc, s53, v71
	s_and_b64 s[68:69], s[0:1], vcc
; __device__ __forceinline__ void attn_item(const Ctx& C, int it, int itn, u32x4 (&kv)[4], u32x4 (&vv)[4], u32x4 (&qv)[2]) {
;     ...
;     const int a = 16 * w + fr;
;     float mx = -1e30f;
; #pragma unroll
;     for (int kt = 0; kt < 9; ++kt)
; #pragma unroll
;         for (int rg = 0; rg < 4; ++rg) { const int cidx = 16 * (w + kt) + 4 * quad + rg, rel = cidx - 64 - a, ik = 128 * jb - 64 + cidx;
;             const bool valid = (rel >= -64) && (rel <= 64) && (ik >= 0) && (ik < n);
;             const int bi = rel < -64 ? 0 : (rel > 64 ? 128 : rel + 64);
;             const float s = valid ? sc[kt][rg] * 0.125f + bt[bi] : -1e30f;
;             sc[kt][rg] = s; mx = fmaxf(mx, s); }
	v_fmac_f32_e32 v212, 0x3e000000, v73
	v_cndmask_b32_e64 v70, v178, v212, s[68:69]
	v_add_u32_e32 v71, s48, v113
	v_readlane_b32 s0, v255, 23
	v_cmp_lt_i32_e32 vcc, -1, v71
	v_readlane_b32 s1, v255, 24
	s_and_b64 s[0:1], s[0:1], vcc
	v_cmp_gt_i32_e32 vcc, s53, v71
	s_and_b64 s[68:69], s[0:1], vcc
	v_fmac_f32_e32 v213, 0x3e000000, v66
	v_cndmask_b32_e64 v72, v178, v213, s[68:69]
	v_add_u32_e32 v66, s48, v115
	v_readlane_b32 s0, v255, 25
	v_cmp_lt_i32_e32 vcc, -1, v66
	v_readlane_b32 s1, v255, 26
	s_and_b64 s[0:1], s[0:1], vcc
	v_cmp_gt_i32_e32 vcc, s53, v66
	s_and_b64 s[68:69], s[0:1], vcc
	v_fmac_f32_e32 v214, 0x3e000000, v67
	v_cndmask_b32_e64 v71, v178, v214, s[68:69]
	v_add_u32_e32 v66, s48, v117
	v_readlane_b32 s0, v255, 27
	v_cmp_lt_i32_e32 vcc, -1, v66
	v_readlane_b32 s1, v255, 28
	s_and_b64 s[0:1], s[0:1], vcc
	v_cmp_gt_i32_e32 vcc, s53, v66
	s_and_b64 s[68:69], s[0:1], vcc
	v_fmac_f32_e32 v215, 0x3e000000, v68
	v_cndmask_b32_e64 v73, v178, v215, s[68:69]
	v_add_u32_e32 v67, s48, v119
	v_readlane_b32 s0, v255, 29
	v_cmp_lt_i32_e32 vcc, -1, v67
	v_readlane_b32 s1, v255, 30
	s_and_b64 s[0:1], s[0:1], vcc
	v_cmp_gt_i32_e32 vcc, s53, v67
	s_and_b64 s[68:69], s[0:1], vcc
	v_fmac_f32_e32 v223, 0x3e000000, v69
	v_cndmask_b32_e64 v66, v178, v223, s[68:69]
	v_add_u32_e32 v67, s48, v121
	v_readlane_b32 s0, v255, 31
	v_cmp_lt_i32_e32 vcc, -1, v67
	v_readlane_b32 s1, v255, 32
	s_and_b64 s[0:1], s[0:1], vcc
	v_cmp_gt_i32_e32 vcc, s53, v67
	s_and_b64 s[68:69], s[0:1], vcc
	v_fmac_f32_e32 v228, 0x3e000000, v60
	v_cndmask_b32_e64 v69, v178, v228, s[68:69]
	v_add_u32_e32 v60, s48, v123
	v_cmp_lt_i32_e32 vcc, -1, v60
	s_and_b64 s[0:1], s[22:23], vcc
	v_cmp_gt_i32_e32 vcc, s53, v60
	s_and_b64 s[68:69], s[0:1], vcc
	v_fmac_f32_e32 v229, 0x3e000000, v61
	v_cndmask_b32_e64 v67, v178, v229, s[68:69]
	v_add_u32_e32 v60, s48, v125
	v_cmp_lt_i32_e32 vcc, -1, v60
	s_and_b64 s[0:1], s[30:31], vcc
	v_cmp_gt_i32_e32 vcc, s53, v60
	s_and_b64 s[68:69], s[0:1], vcc
	v_fmac_f32_e32 v230, 0x3e000000, v62
	v_cndmask_b32_e64 v68, v178, v230, s[68:69]
	v_add_u32_e32 v61, s48, v127
	v_readlane_b32 s0, v255, 33
	v_cmp_lt_i32_e32 vcc, -1, v61
	v_readlane_b32 s1, v255, 34
	s_and_b64 s[0:1], s[0:1], vcc
	v_cmp_gt_i32_e32 vcc, s53, v61
	s_and_b64 s[68:69], s[0:1], vcc
	v_fmac_f32_e32 v231, 0x3e000000, v63
	v_cndmask_b32_e64 v60, v178, v231, s[68:69]
	v_add_u32_e32 v61, s48, v129
	v_readlane_b32 s0, v255, 35
	v_cmp_lt_i32_e32 vcc, -1, v61
	v_readlane_b32 s1, v255, 36
	s_and_b64 s[0:1], s[0:1], vcc
	v_cmp_gt_i32_e32 vcc, s53, v61
	s_and_b64 s[68:69], s[0:1], vcc
	v_fmac_f32_e32 v232, 0x3e000000, v56
	v_cndmask_b32_e64 v62, v178, v232, s[68:69]
	v_add_u32_e32 v56, s48, v131
	v_readlane_b32 s0, v255, 37
	v_cmp_lt_i32_e32 vcc, -1, v56
	v_readlane_b32 s1, v255, 38
	s_and_b64 s[0:1], s[0:1], vcc
	v_cmp_gt_i32_e32 vcc, s53, v56
	s_and_b64 s[68:69], s[0:1], vcc
	v_fmac_f32_e32 v233, 0x3e000000, v57
	v_cndmask_b32_e64 v61, v178, v233, s[68:69]
	v_add_u32_e32 v56, s48, v133
	v_readlane_b32 s0, v255, 39
	v_cmp_lt_i32_e32 vcc, -1, v56
	v_readlane_b32 s1, v255, 40
	s_and_b64 s[0:1], s[0:1], vcc
	v_cmp_gt_i32_e32 vcc, s53, v56
	s_and_b64 s[68:69], s[0:1], vcc
	v_fmac_f32_e32 v234, 0x3e000000, v58
	v_cndmask_b32_e64 v63, v178, v234, s[68:69]
	v_add_u32_e32 v56, s48, v135
	v_readlane_b32 s0, v255, 41
	v_cmp_lt_i32_e32 vcc, -1, v56
	v_readlane_b32 s1, v255, 42
	s_and_b64 s[0:1], s[0:1], vcc
	v_cmp_gt_i32_e32 vcc, s53, v56
	s_and_b64 s[68:69], s[0:1], vcc
	v_fmac_f32_e32 v235, 0x3e000000, v59
	v_cndmask_b32_e64 v57, v178, v235, s[68:69]
	v_add_u32_e32 v56, s48, v137
	v_cmp_lt_i32_e32 vcc, -1, v56
	s_and_b64 s[0:1], s[84:85], vcc
; __device__ __forceinline__ void attn_item(const Ctx& C, int it, int itn, u32x4 (&kv)[4], u32x4 (&vv)[4], u32x4 (&qv)[2]) {
;     ...
;     const int a = 16 * w + fr;
;     float mx = -1e30f;
; #pragma unroll
;     for (int kt = 0; kt < 9; ++kt)
; #pragma unroll
;         for (int rg = 0; rg < 4; ++rg) { const int cidx = 16 * (w + kt) + 4 * quad + rg, rel = cidx - 64 - a, ik = 128 * jb - 64 + cidx;
;             const bool valid = (rel >= -64) && (rel <= 64) && (ik >= 0) && (ik < n);
;             const int bi = rel < -64 ? 0 : (rel > 64 ? 128 : rel + 64);
;             const float s = valid ? sc[kt][rg] * 0.125f + bt[bi] : -1e30f;
;             sc[kt][rg] = s; mx = fmaxf(mx, s); }
	v_cmp_gt_i32_e32 vcc, s53, v56
	s_and_b64 s[68:69], s[0:1], vcc
	v_fmac_f32_e32 v236, 0x3e000000, v52
	v_cndmask_b32_e64 v59, v178, v236, s[68:69]
	v_add_u32_e32 v52, s48, v139
	v_cmp_lt_i32_e32 vcc, -1, v52
	s_and_b64 s[0:1], s[86:87], vcc
	v_cmp_gt_i32_e32 vcc, s53, v52
	s_and_b64 s[68:69], s[0:1], vcc
	v_fmac_f32_e32 v237, 0x3e000000, v53
	v_cndmask_b32_e64 v56, v178, v237, s[68:69]
	v_add_u32_e32 v52, s48, v141
	v_cmp_lt_i32_e32 vcc, -1, v52
	s_and_b64 s[0:1], s[88:89], vcc
	v_cmp_gt_i32_e32 vcc, s53, v52
	s_and_b64 s[68:69], s[0:1], vcc
	v_fmac_f32_e32 v238, 0x3e000000, v54
	v_cndmask_b32_e64 v58, v178, v238, s[68:69]
	v_add_u32_e32 v52, s48, v143
	v_cmp_lt_i32_e32 vcc, -1, v52
	s_and_b64 s[0:1], s[90:91], vcc
	v_cmp_gt_i32_e32 vcc, s53, v52
	s_and_b64 s[68:69], s[0:1], vcc
	v_fmac_f32_e32 v240, 0x3e000000, v55
	v_cndmask_b32_e64 v53, v178, v240, s[68:69]
	v_add_u32_e32 v52, s48, v145
	v_cmp_lt_i32_e32 vcc, -1, v52
	s_and_b64 s[0:1], s[92:93], vcc
	v_cmp_gt_i32_e32 vcc, s53, v52
	s_and_b64 s[68:69], s[0:1], vcc
	v_fmac_f32_e32 v241, 0x3e000000, v48
	v_cndmask_b32_e64 v55, v178, v241, s[68:69]
	v_add_u32_e32 v48, s48, v147
	v_cmp_lt_i32_e32 vcc, -1, v48
	s_and_b64 s[0:1], s[94:95], vcc
	v_cmp_gt_i32_e32 vcc, s53, v48
	s_and_b64 s[68:69], s[0:1], vcc
	v_fmac_f32_e32 v242, 0x3e000000, v49
	v_cndmask_b32_e64 v52, v178, v242, s[68:69]
	v_add_u32_e32 v48, s48, v149
	v_cmp_lt_i32_e32 vcc, -1, v48
	s_and_b64 s[0:1], s[96:97], vcc
	v_cmp_gt_i32_e32 vcc, s53, v48
	s_and_b64 s[68:69], s[0:1], vcc
	v_fmac_f32_e32 v243, 0x3e000000, v50
	v_cndmask_b32_e64 v54, v178, v243, s[68:69]
	v_add_u32_e32 v48, s48, v151
	v_cmp_lt_i32_e32 vcc, -1, v48
	s_and_b64 s[0:1], s[38:39], vcc
	v_cmp_gt_i32_e32 vcc, s53, v48
	s_and_b64 s[68:69], s[0:1], vcc
	v_fmac_f32_e32 v244, 0x3e000000, v51
	v_cndmask_b32_e64 v49, v178, v244, s[68:69]
	v_add_u32_e32 v48, s48, v153
	v_cmp_lt_i32_e32 vcc, -1, v48
	s_and_b64 s[0:1], s[4:5], vcc
	v_cmp_gt_i32_e32 vcc, s53, v48
	s_and_b64 s[68:69], s[0:1], vcc
	v_fmac_f32_e32 v245, 0x3e000000, v44
	v_cndmask_b32_e64 v50, v178, v245, s[68:69]
	v_add_u32_e32 v44, s48, v155
	v_cmp_lt_i32_e32 vcc, -1, v44
	s_and_b64 s[0:1], s[6:7], vcc
	v_cmp_gt_i32_e32 vcc, s53, v44
	s_and_b64 s[68:69], s[0:1], vcc
	v_fmac_f32_e32 v246, 0x3e000000, v45
	v_cndmask_b32_e64 v48, v178, v246, s[68:69]
	v_add_u32_e32 v44, s48, v157
	v_cmp_lt_i32_e32 vcc, -1, v44
	s_and_b64 s[0:1], s[8:9], vcc
	v_cmp_gt_i32_e32 vcc, s53, v44
	s_and_b64 s[68:69], s[0:1], vcc
	v_fmac_f32_e32 v247, 0x3e000000, v46
	v_cndmask_b32_e64 v45, v178, v247, s[68:69]
	v_add_u32_e32 v46, s48, v159
	v_cmp_lt_i32_e32 vcc, -1, v46
	s_and_b64 s[0:1], s[10:11], vcc
	v_cmp_gt_i32_e32 vcc, s53, v46
	s_and_b64 s[68:69], s[0:1], vcc
	v_fmac_f32_e32 v248, 0x3e000000, v47
	v_cndmask_b32_e64 v44, v178, v248, s[68:69]
	v_add_u32_e32 v46, s48, v161
	v_cmp_lt_i32_e32 vcc, -1, v46
	s_and_b64 s[0:1], s[12:13], vcc
	v_cmp_gt_i32_e32 vcc, s53, v46
	s_and_b64 s[68:69], s[0:1], vcc
	v_fmac_f32_e32 v249, 0x3e000000, v40
	v_cndmask_b32_e64 v47, v178, v249, s[68:69]
	v_add_u32_e32 v40, s48, v163
	v_cmp_lt_i32_e32 vcc, -1, v40
	s_and_b64 s[0:1], s[14:15], vcc
	v_cmp_gt_i32_e32 vcc, s53, v40
	s_and_b64 s[68:69], s[0:1], vcc
	v_fmac_f32_e32 v250, 0x3e000000, v41
	v_cndmask_b32_e64 v46, v178, v250, s[68:69]
	v_add_u32_e32 v40, s48, v165
	v_cmp_lt_i32_e32 vcc, -1, v40
	s_and_b64 s[0:1], s[16:17], vcc
	v_cmp_gt_i32_e32 vcc, s53, v40
	s_and_b64 s[68:69], s[0:1], vcc
	v_mov_b32_e32 v41, 0xf149f2ca
	v_mov_b32_e32 v51, 0xf149f2ca
	s_and_saveexec_b64 s[0:1], s[68:69]
	s_cbranch_execz .LBB0_429
	ds_read_b32 v51, v166
	s_waitcnt lgkmcnt(0)
	v_fmac_f32_e32 v51, 0x3e000000, v42
